# v13 + the same one-rendezvous-per-super-phase K-loop restructure applied to P8 (down projection)
# baseline (speedup 1.0000x reference)
; #define PG8_STAGE(bufoff, gbase, voff) do { _Pragma("unroll") for (int _i = 0; _i < 2; ++_i) \
;         __builtin_amdgcn_global_load_lds((const unsigned*)((const char*)(gbase) + (voff)[_i]), (PG8_LAS unsigned*)(lds + (bufoff) + ldsw + _i * 8192), 16, 0, 0); } while (0)
; #define PG8_WAIT_V(n) asm volatile("s_waitcnt vmcnt(" #n ")" ::: "memory")
; #define PG8_BAR __builtin_amdgcn_s_barrier()
; template <class Epi, class Sched, bool ALIGN_EPI = false, bool SP2 = false>
; __device__ __forceinline__ void gemm_phase(PG8_LAS unsigned char* lds, const Gemm g, const Sched& S, const Epi& E) {
;     ...
;     const int tid = tid_, wid = __builtin_amdgcn_readfirstlane(tid >> 6), lane = tid & 63, wr = wid >> 2, wc = wid & 3, fr = lane & 15, fq = lane >> 4;
;     const int K = g.K, nt = K / BK;
;     unsigned voffA[2], voffB[2];
; #pragma unroll
;     for (int i = 0; i < 2; ++i) { int R, C; stage_rc(tid * 16 + i * 8192, R, C); const int Rb = Epi::PERM ? ((R & ~31) + perm32(R & 31)) : R;
;         voffA[i] = (unsigned)(R * K + C) * 2u; voffB[i] = (unsigned)(Rb * K + C) * 2u; }
;     const size_t kstep = (size_t)(BK * 2);
;     const size_t hstep = (size_t)HALF * K * 2;
;     const size_t tstep = 2 * hstep;
;     const unsigned ldsw = (unsigned)wid * 1024u;
;     const int aoff = lds_byte(wr * 64 + fr, fq * 8), boff = lds_byte(wc * 32 + fr, fq * 8);
;     ...
;     const char* cA = (const char*)g.A + (size_t)cur.pm * tstep; const char* cB = (const char*)g.Bt + (size_t)cur.pn * tstep;
;     S.a_ready(cur);
;     if constexpr (SP2) {
;         PG8_STAGE(PG8_SB(0, 0), cB, voffB); PG8_STAGE(PG8_SB(0, 1), cB + hstep, voffB); PG8_STAGE(PG8_SA(0, 0), cA, voffA); PG8_STAGE(PG8_SA(0, 1), cA + hstep, voffA);
;         if (wr == 1) PG8_BAR;
;         PG8_WAIT_V(2); PG8_BAR;
;         PG8_STAGE(PG8_SB(1, 0), cB + kstep, voffB); PG8_STAGE(PG8_SA(1, 0), cA + kstep, voffA); PG8_STAGE(PG8_SB(1, 1), cB + hstep + kstep, voffB);
;         PG8_WAIT_V(6); PG8_BAR;
.LBB0_1076:
	s_add_u32 s6, s96, 0x4d300000
	s_addc_u32 s7, s97, 0
	s_add_u32 s12, s96, 0xb00000
	s_addc_u32 s13, s97, 0
	s_and_b64 vcc, exec, s[4:5]
	s_cbranch_vccnz .LBB0_1112
	v_ashrrev_i32_e32 v2, 31, v10
	v_lshrrev_b32_e32 v2, 26, v2
	v_add_u32_e32 v2, v10, v2
	v_ashrrev_i32_e32 v11, 6, v2
	v_bfe_i32 v2, v10, 27, 1
	v_lshlrev_b32_e32 v1, 4, v10
	v_lshrrev_b32_e32 v2, 22, v2
	v_add_u32_e32 v2, v1, v2
	v_and_b32_e32 v2, 0xfffffc00, v2
	v_sub_u32_e32 v2, v1, v2
	v_lshrrev_b32_e32 v3, 4, v2
	v_bitop3_b32 v2, v3, v2, 32 bitop3:0x6c
	v_ashrrev_i32_e32 v4, 31, v2
	v_lshrrev_b32_e32 v4, 26, v4
	v_add_u32_e32 v4, v2, v4
	v_lshlrev_b32_e32 v3, 3, v11
	v_ashrrev_i32_e32 v12, 6, v4
	v_and_b32_e32 v4, 0xc0, v4
	v_and_b32_e32 v3, -16, v3
	v_sub_u32_e32 v2, v2, v4
	v_mov_b32_e32 v4, 1
	v_add_u32_e32 v3, v12, v3
	v_ashrrev_i16_sdwa v2, v4, sext(v2) dst_sel:DWORD dst_unused:UNUSED_PAD src0_sel:DWORD src1_sel:BYTE_0
	v_lshlrev_b32_e32 v5, 5, v11
	v_bfe_i32 v13, v2, 0, 16
	v_lshlrev_b32_e32 v2, 1, v3
	v_lshrrev_b32_e32 v6, 2, v3
	v_and_b32_e32 v7, 3, v12
	s_mov_b32 s1, 0x1ffe0
	v_and_b32_e32 v5, 32, v5
	v_and_b32_e32 v2, 24, v2
	v_and_b32_e32 v6, 4, v6
	v_and_or_b32 v7, v3, s1, v7
	v_or3_b32 v2, v7, v6, v2
	v_add_lshl_u32 v5, v5, v13, 1
	v_add_u32_e32 v1, 0x2000, v1
	v_lshl_add_u32 v132, v2, 15, v5
	v_ashrrev_i32_e32 v2, 31, v1
	v_lshrrev_b32_e32 v2, 22, v2
	v_add_u32_e32 v2, v1, v2
	v_ashrrev_i32_e32 v14, 10, v2
	v_mul_i32_i24_e32 v2, 0x400, v14
	v_sub_u32_e32 v1, v1, v2
	v_lshrrev_b32_e32 v2, 4, v1
	v_bitop3_b32 v1, v2, v1, 32 bitop3:0x6c
	v_lshl_add_u32 v130, v3, 15, v5
	v_ashrrev_i32_e32 v3, 31, v1
	v_lshrrev_b32_e32 v3, 26, v3
	v_add_u32_e32 v3, v1, v3
	v_lshlrev_b32_e32 v2, 3, v14
	v_ashrrev_i32_e32 v15, 6, v3
	v_and_b32_e32 v3, 0xc0, v3
	v_and_b32_e32 v2, -16, v2
	v_sub_u32_e32 v1, v1, v3
	s_ashr_i32 s0, s20, 6
	v_add_u32_e32 v2, v15, v2
	v_ashrrev_i16_sdwa v1, v4, sext(v1) dst_sel:DWORD dst_unused:UNUSED_PAD src0_sel:DWORD src1_sel:BYTE_0
	v_and_b32_e32 v4, 3, v15
	s_ashr_i32 s35, s34, 31
	s_ashr_i32 s31, s30, 31
	v_and_or_b32 v4, v2, s1, v4
	s_ashr_i32 s1, s20, 8
	s_lshl_b32 s33, s0, 10
	s_lshl_b64 s[4:5], s[34:35], 23
	s_lshl_b64 s[14:15], s[30:31], 23
	s_add_u32 s38, s70, s14
	v_lshlrev_b32_e32 v5, 5, v14
	v_bfe_i32 v16, v1, 0, 16
	v_lshlrev_b32_e32 v1, 1, v2
	v_lshrrev_b32_e32 v3, 2, v2
	s_addc_u32 s39, s71, s15
	s_add_i32 s42, s33, 0
	v_and_b32_e32 v5, 32, v5
	v_and_b32_e32 v1, 24, v1
	v_and_b32_e32 v3, 4, v3
	s_add_i32 m0, s42, 0x10000
	v_or3_b32 v1, v4, v3, v1
	v_add_lshl_u32 v3, v5, v16, 1
	global_load_lds_dwordx4 v132, s[38:39]
	s_add_i32 m0, s42, 0x12000
	v_lshl_add_u32 v136, v1, 15, v3
	s_add_u32 s14, s38, 0x400000
	global_load_lds_dwordx4 v136, s[38:39]
	s_addc_u32 s15, s39, 0
	s_add_i32 m0, s42, 0x14000
	v_lshl_add_u32 v134, v2, 15, v3
	global_load_lds_dwordx4 v132, s[14:15]
	s_add_i32 m0, s42, 0x16000
	s_add_u32 s36, s80, s4
	s_addc_u32 s37, s81, s5
	s_add_i32 s43, s42, 0x2000
	global_load_lds_dwordx4 v136, s[14:15]
	s_mov_b32 m0, s42
	s_add_u32 s4, s36, 0x400000
	global_load_lds_dwordx4 v130, s[36:37]
	s_mov_b32 m0, s43
	s_addc_u32 s5, s37, 0
	s_add_i32 s44, s42, 0x4000
	global_load_lds_dwordx4 v134, s[36:37]
	s_mov_b32 m0, s44
	s_add_i32 s45, s42, 0x6000
	global_load_lds_dwordx4 v130, s[4:5]
	s_mov_b32 m0, s45
	v_mov_b32_e32 v133, 0
	global_load_lds_dwordx4 v134, s[4:5]
	v_mov_b32_e32 v137, v133
	v_mov_b32_e32 v131, v133
	v_mov_b32_e32 v135, v133
	s_cmp_eq_u32 s1, 1
	s_mov_b32 s46, 0
	v_lshl_add_u64 v[8:9], s[38:39], 0, v[132:133]
	v_lshl_add_u64 v[6:7], s[38:39], 0, v[136:137]
	v_lshl_add_u64 v[2:3], s[36:37], 0, v[130:131]
	s_cselect_b64 s[14:15], -1, 0
	s_cmp_lg_u32 s1, 1
	v_lshl_add_u64 v[4:5], s[36:37], 0, v[134:135]
	s_cbranch_scc1 .LBB0_1079
.LBB0_1079:
	s_mov_b64 s[18:19], 0x80
	s_and_b32 s47, s0, 3
	s_add_i32 m0, s42, 0x18000
	v_lshl_add_u64 v[8:9], v[8:9], 0, s[18:19]
	s_lshl_b32 s0, s1, 13
	s_lshl_b32 s21, s47, 12
	s_waitcnt vmcnt(2)
	s_barrier
	global_load_lds_dwordx4 v[8:9], off
	v_lshl_add_u64 v[6:7], v[6:7], 0, s[18:19]
	s_add_i32 m0, s42, 0x1a000
	s_add_i32 s48, s42, 0x8000
	s_add_i32 s49, s42, 0xa000
	global_load_lds_dwordx4 v[6:7], off
	v_lshl_add_u64 v[2:3], v[2:3], 0, s[18:19]
	s_mov_b32 m0, s48
	s_add_u32 s4, s38, 0x400080
	global_load_lds_dwordx4 v[2:3], off
	v_lshl_add_u64 v[2:3], v[4:5], 0, s[18:19]
	s_mov_b32 m0, s49
	s_addc_u32 s5, s39, 0
	global_load_lds_dwordx4 v[2:3], off
	s_add_i32 m0, s42, 0x1c000
	v_lshl_add_u64 v[2:3], s[4:5], 0, v[132:133]
	global_load_lds_dwordx4 v[2:3], off
	v_lshl_add_u64 v[2:3], s[4:5], 0, v[136:137]
	s_add_i32 m0, s42, 0x1e000
	s_cmpk_lt_u32 s20, 0x100
	global_load_lds_dwordx4 v[2:3], off
	v_bfe_u32 v2, v10, 4, 2
	v_and_b32_e32 v3, 15, v10
	v_lshlrev_b32_e32 v5, 4, v2
	v_lshl_or_b32 v1, s1, 6, v3
	v_lshl_or_b32 v3, v3, 6, v5
	v_lshlrev_b32_e32 v5, 2, v10
	v_and_b32_e32 v5, 32, v5
	v_lshlrev_b32_e32 v4, 3, v2
	v_bitop3_b32 v6, v3, s0, v5 bitop3:0xde
	v_cmp_eq_u32_e64 s[0:1], 0, v2
	v_lshlrev_b32_e32 v2, 18, v11
	v_and_b32_e32 v2, 0xfff80000, v2
	v_bitop3_b32 v150, v3, s21, v5 bitop3:0xde
	v_lshl_add_u32 v2, v12, 15, v2
	v_and_b32_e32 v3, 1, v11
	v_lshl_or_b32 v2, v3, 6, v2
	v_lshl_add_u32 v138, v13, 1, v2
	v_lshlrev_b32_e32 v2, 18, v14
	v_and_b32_e32 v2, 0xfff80000, v2
	s_waitcnt vmcnt(6)
	v_lshl_add_u32 v2, v15, 15, v2
	v_and_b32_e32 v3, 1, v14
	s_cselect_b64 s[20:21], -1, 0
	v_lshl_or_b32 v2, v3, 6, v2
	s_add_i32 s50, 0, 0x10000
	s_add_i32 s51, 0, 0x14000
	v_lshl_or_b32 v151, s47, 5, v4
	v_mov_b32_e32 v139, v133
	v_lshl_add_u32 v140, v16, 1, v2
	v_mov_b32_e32 v141, v133
	v_mov_b64_e32 v[142:143], 0x400
	v_mov_b64_e32 v[144:145], 0x3ff
	v_add_u32_e32 v152, s50, v150
	v_add_u32_e32 v153, s51, v150
	v_add_u32_e32 v154, 0, v6
	v_mbcnt_hi_u32_b32 v155, -1, v217
	s_barrier
	s_branch .LBB0_1082

; #define PG8_STAGE(bufoff, gbase, voff) do { _Pragma("unroll") for (int _i = 0; _i < 2; ++_i) \
;         __builtin_amdgcn_global_load_lds((const unsigned*)((const char*)(gbase) + (voff)[_i]), (PG8_LAS unsigned*)(lds + (bufoff) + ldsw + _i * 8192), 16, 0, 0); } while (0)
; #define PG8_LDA(dst, b, h) do { _Pragma("unroll") for (int m = 0; m < 4; ++m) _Pragma("unroll") for (int k = 0; k < 2; ++k) dst[m][k] = *(const PG8_LAS bf16x8*)(lds + PG8_SA(b, h) + aoff + m * 2048 + k * 1024); } while (0)
; #define PG8_LDB(dst, b, h) do { _Pragma("unroll") for (int n = 0; n < 2; ++n) _Pragma("unroll") for (int k = 0; k < 2; ++k) dst[n][k] = *(const PG8_LAS bf16x8*)(lds + PG8_SB(b, h) + boff + n * 2048 + k * 1024); } while (0)
; #define PG8_WAIT_V(n) asm volatile("s_waitcnt vmcnt(" #n ")" ::: "memory")
; #define PG8_WAIT_L(n) asm volatile("s_waitcnt lgkmcnt(" #n ")" ::: "memory")
; #define PG8_BAR __builtin_amdgcn_s_barrier()
; template <class Epi, class Sched, bool ALIGN_EPI = false, bool SP2 = false>
; __device__ __forceinline__ void gemm_phase(PG8_LAS unsigned char* lds, const Gemm g, const Sched& S, const Epi& E) {
;     ...
;         const bool has_next = S.next(ui + 1, nxt);
;         const char* nA = has_next ? (const char*)g.A + (size_t)nxt.pm * tstep : cA; const char* nB = has_next ? (const char*)g.Bt + (size_t)nxt.pn * tstep : cB;
;         for (int t = 0; t < nt; t += 2) {
;             const bool last = (t == nt - 2);
;             const char* a1 = cA + (size_t)(t + 1) * kstep;
;             const char* a2 = last ? nA : cA + (size_t)(t + 2) * kstep; const char* b2 = last ? nB : cB + (size_t)(t + 2) * kstep;
;             const char* a3 = a2 + kstep; const char* b3 = b2 + kstep;
;             if (last && has_next) S.a_ready(nxt);
;             if constexpr (SP2) {
;             PG8_LDB(B0, 0, 0); PG8_LDB(B1, 0, 1); PG8_SCHED; PG8_LDA(At, 0, 0); PG8_STAGE(PG8_SA(1, 1), a1 + hstep, voffA);
;             PG8_WAIT_V(8); PG8_WAIT_L(0); PG8_BAR; PG8_MMA(0, 0, At, B0); PG8_MMA(0, 1, At, B1); PG8_BAR; PG8_SCHED;
;     ...
; #pragma unroll
;         for (int a = 0; a < 2; ++a)
; #pragma unroll
;             for (int b = 0; b < 2; ++b)
; #pragma unroll
;                 for (int m = 0; m < 4; ++m)
; #pragma unroll
;                     for (int n = 0; n < 2; ++n) acc[a][b][m][n] = (f32x4){0.f, 0.f, 0.f, 0.f};
;         cur = nxt; cA = nA; cB = nB; ++ui;
.LBB0_1088:
	s_ashr_i32 s25, s24, 31
	s_lshl_b64 s[26:27], s[24:25], 23
	s_add_u32 s26, s80, s26
	s_addc_u32 s27, s81, s27
	s_and_b64 s[28:29], s[4:5], exec
	s_cselect_b32 s25, s27, s37
	s_cselect_b32 s31, s26, s36
	s_ashr_i32 s23, s22, 31
	s_lshl_b64 s[28:29], s[22:23], 23
	s_add_u32 s28, s70, s28
	s_addc_u32 s29, s71, s29
	s_and_b64 s[40:41], s[4:5], exec
	s_cselect_b32 s23, s29, s39
	s_cselect_b32 s35, s28, s38
	s_add_u32 s36, s36, 0x400080
	s_addc_u32 s37, s37, 0
	s_add_u32 s52, s38, 0x100
	v_mov_b32_e32 v2, 0
	s_addc_u32 s53, s39, 0
	s_mov_b32 s54, -2
	v_mov_b32_e32 v3, v2
	v_mov_b32_e32 v4, v2
	v_mov_b32_e32 v5, v2
	v_mov_b32_e32 v6, v2
	s_waitcnt lgkmcnt(0)
	v_mov_b32_e32 v7, v2
	v_mov_b32_e32 v8, v2
	v_mov_b32_e32 v9, v2
	v_mov_b32_e32 v18, v2
	v_mov_b32_e32 v19, v2
	v_mov_b32_e32 v20, v2
	v_mov_b32_e32 v21, v2
	v_mov_b32_e32 v22, v2
	v_mov_b32_e32 v23, v2
	v_mov_b32_e32 v24, v2
	v_mov_b32_e32 v25, v2
	v_mov_b32_e32 v34, v2
	v_mov_b32_e32 v35, v2
	v_mov_b32_e32 v36, v2
	v_mov_b32_e32 v37, v2
	v_mov_b32_e32 v38, v2
	v_mov_b32_e32 v39, v2
	v_mov_b32_e32 v40, v2
	v_mov_b32_e32 v41, v2
	v_mov_b32_e32 v50, v2
	v_mov_b32_e32 v51, v2
	v_mov_b32_e32 v52, v2
	v_mov_b32_e32 v53, v2
	v_mov_b32_e32 v54, v2
	v_mov_b32_e32 v55, v2
	v_mov_b32_e32 v56, v2
	v_mov_b32_e32 v57, v2
	v_mov_b32_e32 v10, v2
	v_mov_b32_e32 v11, v2
	v_mov_b32_e32 v12, v2
	v_mov_b32_e32 v13, v2
	v_mov_b32_e32 v14, v2
	v_mov_b32_e32 v15, v2
	v_mov_b32_e32 v16, v2
	v_mov_b32_e32 v17, v2
	v_mov_b32_e32 v26, v2
	v_mov_b32_e32 v27, v2
	v_mov_b32_e32 v28, v2
	v_mov_b32_e32 v29, v2
	v_mov_b32_e32 v30, v2
	v_mov_b32_e32 v31, v2
	v_mov_b32_e32 v32, v2
	v_mov_b32_e32 v33, v2
	v_mov_b32_e32 v42, v2
	v_mov_b32_e32 v43, v2
	v_mov_b32_e32 v44, v2
	v_mov_b32_e32 v45, v2
	v_mov_b32_e32 v46, v2
	v_mov_b32_e32 v47, v2
	v_mov_b32_e32 v48, v2
	v_mov_b32_e32 v49, v2
	v_mov_b32_e32 v58, v2
	v_mov_b32_e32 v59, v2
	v_mov_b32_e32 v60, v2
	v_mov_b32_e32 v61, v2
	v_mov_b32_e32 v62, v2
	v_mov_b32_e32 v63, v2
	v_mov_b32_e32 v64, v2
	v_mov_b32_e32 v65, v2
	v_mov_b32_e32 v66, v2
	v_mov_b32_e32 v67, v2
	v_mov_b32_e32 v68, v2
	v_mov_b32_e32 v69, v2
	v_mov_b32_e32 v70, v2
	v_mov_b32_e32 v71, v2
	v_mov_b32_e32 v72, v2
	v_mov_b32_e32 v73, v2
	v_mov_b32_e32 v82, v2
	v_mov_b32_e32 v83, v2
	v_mov_b32_e32 v84, v2
	v_mov_b32_e32 v85, v2
	v_mov_b32_e32 v86, v2
	v_mov_b32_e32 v87, v2
	v_mov_b32_e32 v88, v2
	v_mov_b32_e32 v89, v2
	v_mov_b32_e32 v98, v2
	v_mov_b32_e32 v99, v2
	v_mov_b32_e32 v100, v2
	v_mov_b32_e32 v101, v2
	v_mov_b32_e32 v102, v2
	v_mov_b32_e32 v103, v2
	v_mov_b32_e32 v104, v2
	v_mov_b32_e32 v105, v2
	v_mov_b32_e32 v114, v2
	v_mov_b32_e32 v115, v2
	v_mov_b32_e32 v116, v2
	v_mov_b32_e32 v117, v2
	v_mov_b32_e32 v118, v2
	v_mov_b32_e32 v119, v2
	v_mov_b32_e32 v120, v2
	v_mov_b32_e32 v121, v2
	v_mov_b32_e32 v74, v2
	v_mov_b32_e32 v75, v2
	v_mov_b32_e32 v76, v2
	v_mov_b32_e32 v77, v2
	v_mov_b32_e32 v78, v2
	v_mov_b32_e32 v79, v2
	v_mov_b32_e32 v80, v2
	v_mov_b32_e32 v81, v2
	v_mov_b32_e32 v90, v2
	v_mov_b32_e32 v91, v2
	v_mov_b32_e32 v92, v2
	v_mov_b32_e32 v93, v2
	v_mov_b32_e32 v94, v2
	v_mov_b32_e32 v95, v2
	v_mov_b32_e32 v96, v2
	v_mov_b32_e32 v97, v2
	v_mov_b32_e32 v106, v2
	v_mov_b32_e32 v107, v2
	v_mov_b32_e32 v108, v2
	v_mov_b32_e32 v109, v2
	v_mov_b32_e32 v110, v2
	v_mov_b32_e32 v111, v2
	v_mov_b32_e32 v112, v2
	v_mov_b32_e32 v113, v2
	v_mov_b32_e32 v122, v2
	v_mov_b32_e32 v123, v2
	v_mov_b32_e32 v124, v2
	v_mov_b32_e32 v125, v2
	v_mov_b32_e32 v126, v2
	v_mov_b32_e32 v127, v2
	v_mov_b32_e32 v128, v2
	v_mov_b32_e32 v129, v2
	s_cmp_lg_u32 s20, 0
	s_cbranch_scc0 .Lmy_p8_trail
.LBB0_1089:
	ds_read_b128 v[146:149], v152
	ds_read_b128 v[156:159], v152 offset:1024
	ds_read_b128 v[160:163], v152 offset:2048
	ds_read_b128 v[164:167], v152 offset:3072
	ds_read_b128 v[168:171], v153
	ds_read_b128 v[172:175], v153 offset:1024
	ds_read_b128 v[176:179], v153 offset:2048
	ds_read_b128 v[180:183], v153 offset:3072
	s_add_u32 s38, s36, 0xffc00080
	s_addc_u32 s39, s37, -1
	s_cmpk_eq_i32 s54, 0xfc
	s_cselect_b32 s41, s25, s39
	s_cselect_b32 s40, s31, s38
	s_cselect_b32 s39, s23, s53
	s_cselect_b32 s38, s35, s52
	v_lshl_add_u64 v[218:219], s[36:37], 0, v[138:139]
	s_add_i32 m0, s42, 0xc000
	ds_read_b128 v[184:187], v154
	ds_read_b128 v[188:191], v154 offset:1024
	ds_read_b128 v[192:195], v154 offset:2048
	ds_read_b128 v[196:199], v154 offset:3072
	ds_read_b128 v[200:203], v154 offset:4096
	ds_read_b128 v[204:207], v154 offset:5120
	ds_read_b128 v[208:211], v154 offset:6144
	ds_read_b128 v[212:215], v154 offset:7168
	global_load_lds_dwordx4 v[218:219], off
	v_lshl_add_u64 v[218:219], s[36:37], 0, v[140:141]
	s_add_i32 m0, s42, 0xe000
	s_nop 0
	global_load_lds_dwordx4 v[218:219], off
	s_waitcnt vmcnt(8)
	s_waitcnt lgkmcnt(0)
	s_setprio 1
	v_mfma_f32_16x16x32_bf16 v[126:129], v[146:149], v[184:187], v[126:129]
	v_mfma_f32_16x16x32_bf16 v[122:125], v[160:163], v[184:187], v[122:125]
	v_mfma_f32_16x16x32_bf16 v[110:113], v[146:149], v[192:195], v[110:113]
	v_mfma_f32_16x16x32_bf16 v[106:109], v[160:163], v[192:195], v[106:109]
	v_mfma_f32_16x16x32_bf16 v[94:97], v[146:149], v[200:203], v[94:97]
	v_mfma_f32_16x16x32_bf16 v[90:93], v[160:163], v[200:203], v[90:93]
	v_mfma_f32_16x16x32_bf16 v[78:81], v[146:149], v[208:211], v[78:81]
	v_mfma_f32_16x16x32_bf16 v[74:77], v[160:163], v[208:211], v[74:77]
	v_mfma_f32_16x16x32_bf16 v[126:129], v[156:159], v[188:191], v[126:129]
	v_mfma_f32_16x16x32_bf16 v[122:125], v[164:167], v[188:191], v[122:125]
	v_mfma_f32_16x16x32_bf16 v[110:113], v[156:159], v[196:199], v[110:113]
	v_mfma_f32_16x16x32_bf16 v[106:109], v[164:167], v[196:199], v[106:109]
	v_mfma_f32_16x16x32_bf16 v[94:97], v[156:159], v[204:207], v[94:97]
	v_mfma_f32_16x16x32_bf16 v[90:93], v[164:167], v[204:207], v[90:93]
	v_mfma_f32_16x16x32_bf16 v[78:81], v[156:159], v[212:215], v[78:81]
	v_mfma_f32_16x16x32_bf16 v[74:77], v[164:167], v[212:215], v[74:77]
	s_setprio 2
	v_mfma_f32_16x16x32_bf16 v[118:121], v[168:171], v[184:187], v[118:121]
	v_mfma_f32_16x16x32_bf16 v[114:117], v[176:179], v[184:187], v[114:117]
	v_mfma_f32_16x16x32_bf16 v[102:105], v[168:171], v[192:195], v[102:105]
	v_mfma_f32_16x16x32_bf16 v[98:101], v[176:179], v[192:195], v[98:101]
	v_mfma_f32_16x16x32_bf16 v[86:89], v[168:171], v[200:203], v[86:89]
	v_mfma_f32_16x16x32_bf16 v[82:85], v[176:179], v[200:203], v[82:85]
	v_mfma_f32_16x16x32_bf16 v[70:73], v[168:171], v[208:211], v[70:73]
	v_mfma_f32_16x16x32_bf16 v[66:69], v[176:179], v[208:211], v[66:69]
	v_mfma_f32_16x16x32_bf16 v[118:121], v[172:175], v[188:191], v[118:121]
	v_mfma_f32_16x16x32_bf16 v[114:117], v[180:183], v[188:191], v[114:117]
	v_mfma_f32_16x16x32_bf16 v[102:105], v[172:175], v[196:199], v[102:105]
	v_mfma_f32_16x16x32_bf16 v[98:101], v[180:183], v[196:199], v[98:101]
	v_mfma_f32_16x16x32_bf16 v[86:89], v[172:175], v[204:207], v[86:89]
	v_mfma_f32_16x16x32_bf16 v[82:85], v[180:183], v[204:207], v[82:85]
	v_mfma_f32_16x16x32_bf16 v[70:73], v[172:175], v[212:215], v[70:73]
	v_mfma_f32_16x16x32_bf16 v[66:69], v[180:183], v[212:215], v[66:69]
	s_barrier
; #define PG8_STAGE(bufoff, gbase, voff) do { _Pragma("unroll") for (int _i = 0; _i < 2; ++_i) \
;         __builtin_amdgcn_global_load_lds((const unsigned*)((const char*)(gbase) + (voff)[_i]), (PG8_LAS unsigned*)(lds + (bufoff) + ldsw + _i * 8192), 16, 0, 0); } while (0)
; #define PG8_LDA(dst, b, h) do { _Pragma("unroll") for (int m = 0; m < 4; ++m) _Pragma("unroll") for (int k = 0; k < 2; ++k) dst[m][k] = *(const PG8_LAS bf16x8*)(lds + PG8_SA(b, h) + aoff + m * 2048 + k * 1024); } while (0)
; #define PG8_LDB(dst, b, h) do { _Pragma("unroll") for (int n = 0; n < 2; ++n) _Pragma("unroll") for (int k = 0; k < 2; ++k) dst[n][k] = *(const PG8_LAS bf16x8*)(lds + PG8_SB(b, h) + boff + n * 2048 + k * 1024); } while (0)
; #define PG8_MMA(ai, bj, At, Bt) do { __builtin_amdgcn_s_setprio(1); _Pragma("unroll") for (int m = 0; m < 4; ++m) _Pragma("unroll") for (int n = 0; n < 2; ++n) _Pragma("unroll") for (int k = 0; k < 2; ++k) \
;         acc[ai][bj][m][n] = __builtin_amdgcn_mfma_f32_16x16x32_bf16(Bt[n][k], At[m][k], acc[ai][bj][m][n], 0, 0, 0); __builtin_amdgcn_s_setprio(0); } while (0)
; #define PG8_WAIT_V(n) asm volatile("s_waitcnt vmcnt(" #n ")" ::: "memory")
; #define PG8_WAIT_L(n) asm volatile("s_waitcnt lgkmcnt(" #n ")" ::: "memory")
; #define PG8_BAR __builtin_amdgcn_s_barrier()
; #define PG8_SCHED __builtin_amdgcn_sched_barrier(0)
; template <class Epi, class Sched, bool ALIGN_EPI = false, bool SP2 = false>
; __device__ __forceinline__ void gemm_phase(PG8_LAS unsigned char* lds, const Gemm g, const Sched& S, const Epi& E) {
;     ...
;             PG8_LDA(At, 0, 1); PG8_STAGE(PG8_SB(0, 0), b2, voffB); PG8_STAGE(PG8_SB(0, 1), b2 + hstep, voffB); PG8_STAGE(PG8_SA(0, 0), a2, voffA);
;             PG8_WAIT_V(8); PG8_WAIT_L(0); PG8_BAR; PG8_MMA(1, 0, At, B0); PG8_MMA(1, 1, At, B1); PG8_BAR; PG8_SCHED;
;             PG8_LDB(B0, 1, 0); PG8_LDB(B1, 1, 1); PG8_SCHED; PG8_LDA(At, 1, 0); PG8_STAGE(PG8_SA(0, 1), a2 + hstep, voffA);
;             PG8_WAIT_V(8); PG8_WAIT_L(0); PG8_BAR; PG8_MMA(0, 0, At, B0); PG8_MMA(0, 1, At, B1); PG8_BAR; PG8_SCHED;
	s_setprio 0
	s_add_i32 s55, s50, s33
	v_lshl_add_u64 v[218:219], s[38:39], 0, v[132:133]
	s_mov_b32 m0, s55
	ds_read_b128 v[184:187], v154 offset:16384
	ds_read_b128 v[188:191], v154 offset:17408
	ds_read_b128 v[192:195], v154 offset:18432
	ds_read_b128 v[196:199], v154 offset:19456
	ds_read_b128 v[200:203], v154 offset:20480
	ds_read_b128 v[204:207], v154 offset:21504
	ds_read_b128 v[208:211], v154 offset:22528
	ds_read_b128 v[212:215], v154 offset:23552
	global_load_lds_dwordx4 v[218:219], off
	s_add_i32 m0, s55, 0x2000
	s_add_u32 s56, s38, 0x400000
	v_lshl_add_u64 v[220:221], s[38:39], 0, v[136:137]
	s_addc_u32 s57, s39, 0
	s_add_i32 s55, s51, s33
	global_load_lds_dwordx4 v[220:221], off
	v_lshl_add_u64 v[222:223], s[56:57], 0, v[132:133]
	s_mov_b32 m0, s55
	v_lshl_add_u64 v[224:225], s[40:41], 0, v[134:135]
	global_load_lds_dwordx4 v[222:223], off
	v_lshl_add_u64 v[222:223], s[56:57], 0, v[136:137]
	s_add_i32 m0, s55, 0x2000
	s_nop 0
	global_load_lds_dwordx4 v[222:223], off
	v_lshl_add_u64 v[222:223], s[40:41], 0, v[130:131]
	s_mov_b32 m0, s42
	s_nop 0
	global_load_lds_dwordx4 v[222:223], off
	s_mov_b32 m0, s43
	s_nop 0
	global_load_lds_dwordx4 v[224:225], off
	s_waitcnt vmcnt(8)
	s_waitcnt lgkmcnt(0)
	s_setprio 1
	v_mfma_f32_16x16x32_bf16 v[62:65], v[146:149], v[184:187], v[62:65]
	v_mfma_f32_16x16x32_bf16 v[58:61], v[160:163], v[184:187], v[58:61]
	v_mfma_f32_16x16x32_bf16 v[46:49], v[146:149], v[192:195], v[46:49]
	v_mfma_f32_16x16x32_bf16 v[42:45], v[160:163], v[192:195], v[42:45]
	v_mfma_f32_16x16x32_bf16 v[30:33], v[146:149], v[200:203], v[30:33]
	v_mfma_f32_16x16x32_bf16 v[26:29], v[160:163], v[200:203], v[26:29]
	v_mfma_f32_16x16x32_bf16 v[14:17], v[146:149], v[208:211], v[14:17]
	v_mfma_f32_16x16x32_bf16 v[10:13], v[160:163], v[208:211], v[10:13]
	v_mfma_f32_16x16x32_bf16 v[62:65], v[156:159], v[188:191], v[62:65]
	v_mfma_f32_16x16x32_bf16 v[58:61], v[164:167], v[188:191], v[58:61]
	v_mfma_f32_16x16x32_bf16 v[46:49], v[156:159], v[196:199], v[46:49]
	v_mfma_f32_16x16x32_bf16 v[42:45], v[164:167], v[196:199], v[42:45]
	v_mfma_f32_16x16x32_bf16 v[30:33], v[156:159], v[204:207], v[30:33]
	v_mfma_f32_16x16x32_bf16 v[26:29], v[164:167], v[204:207], v[26:29]
	v_mfma_f32_16x16x32_bf16 v[14:17], v[156:159], v[212:215], v[14:17]
	v_mfma_f32_16x16x32_bf16 v[10:13], v[164:167], v[212:215], v[10:13]
	s_setprio 2
	v_mfma_f32_16x16x32_bf16 v[54:57], v[168:171], v[184:187], v[54:57]
	v_mfma_f32_16x16x32_bf16 v[50:53], v[176:179], v[184:187], v[50:53]
	v_mfma_f32_16x16x32_bf16 v[38:41], v[168:171], v[192:195], v[38:41]
	v_mfma_f32_16x16x32_bf16 v[34:37], v[176:179], v[192:195], v[34:37]
	v_mfma_f32_16x16x32_bf16 v[22:25], v[168:171], v[200:203], v[22:25]
	v_mfma_f32_16x16x32_bf16 v[18:21], v[176:179], v[200:203], v[18:21]
	v_mfma_f32_16x16x32_bf16 v[6:9], v[168:171], v[208:211], v[6:9]
	v_mfma_f32_16x16x32_bf16 v[2:5], v[176:179], v[208:211], v[2:5]
	v_mfma_f32_16x16x32_bf16 v[54:57], v[172:175], v[188:191], v[54:57]
	v_mfma_f32_16x16x32_bf16 v[50:53], v[180:183], v[188:191], v[50:53]
	v_mfma_f32_16x16x32_bf16 v[38:41], v[172:175], v[196:199], v[38:41]
	v_mfma_f32_16x16x32_bf16 v[34:37], v[180:183], v[196:199], v[34:37]
	v_mfma_f32_16x16x32_bf16 v[22:25], v[172:175], v[204:207], v[22:25]
	v_mfma_f32_16x16x32_bf16 v[18:21], v[180:183], v[204:207], v[18:21]
	v_mfma_f32_16x16x32_bf16 v[6:9], v[172:175], v[212:215], v[6:9]
	v_mfma_f32_16x16x32_bf16 v[2:5], v[180:183], v[212:215], v[2:5]
	s_barrier
	s_setprio 0
	s_add_i32 s55, 0, 0x18000
	s_add_i32 s56, 0, 0x1c000
	v_add_u32_e32 v164, s55, v150
	v_add_u32_e32 v180, s56, v150
	ds_read_b128 v[146:149], v164
	ds_read_b128 v[156:159], v164 offset:1024
	ds_read_b128 v[160:163], v164 offset:2048
	ds_read_b128 v[164:167], v164 offset:3072
	ds_read_b128 v[168:171], v180
	ds_read_b128 v[172:175], v180 offset:1024
	ds_read_b128 v[176:179], v180 offset:2048
	ds_read_b128 v[180:183], v180 offset:3072
	s_add_u32 s40, s40, 0x400000
	s_addc_u32 s41, s41, 0
	s_mov_b32 m0, s44
	v_lshl_add_u64 v[226:227], s[40:41], 0, v[130:131]
	ds_read_b128 v[184:187], v154 offset:32768
	ds_read_b128 v[188:191], v154 offset:33792
	ds_read_b128 v[192:195], v154 offset:34816
	ds_read_b128 v[196:199], v154 offset:35840
	ds_read_b128 v[200:203], v154 offset:36864
	ds_read_b128 v[204:207], v154 offset:37888
	ds_read_b128 v[208:211], v154 offset:38912
	ds_read_b128 v[212:215], v154 offset:39936
	global_load_lds_dwordx4 v[226:227], off
	v_lshl_add_u64 v[226:227], s[40:41], 0, v[134:135]
	s_mov_b32 m0, s45
	s_nop 0
	global_load_lds_dwordx4 v[226:227], off
	s_waitcnt vmcnt(8)
	s_waitcnt lgkmcnt(0)
	s_setprio 1
	v_mfma_f32_16x16x32_bf16 v[126:129], v[146:149], v[184:187], v[126:129]
	v_mfma_f32_16x16x32_bf16 v[122:125], v[160:163], v[184:187], v[122:125]
	v_mfma_f32_16x16x32_bf16 v[110:113], v[146:149], v[192:195], v[110:113]
	v_mfma_f32_16x16x32_bf16 v[106:109], v[160:163], v[192:195], v[106:109]
	v_mfma_f32_16x16x32_bf16 v[94:97], v[146:149], v[200:203], v[94:97]
	v_mfma_f32_16x16x32_bf16 v[90:93], v[160:163], v[200:203], v[90:93]
	v_mfma_f32_16x16x32_bf16 v[78:81], v[146:149], v[208:211], v[78:81]
	v_mfma_f32_16x16x32_bf16 v[74:77], v[160:163], v[208:211], v[74:77]
	v_mfma_f32_16x16x32_bf16 v[126:129], v[156:159], v[188:191], v[126:129]
	v_mfma_f32_16x16x32_bf16 v[122:125], v[164:167], v[188:191], v[122:125]
	v_mfma_f32_16x16x32_bf16 v[110:113], v[156:159], v[196:199], v[110:113]
	v_mfma_f32_16x16x32_bf16 v[106:109], v[164:167], v[196:199], v[106:109]
	v_mfma_f32_16x16x32_bf16 v[94:97], v[156:159], v[204:207], v[94:97]
	v_mfma_f32_16x16x32_bf16 v[90:93], v[164:167], v[204:207], v[90:93]
	v_mfma_f32_16x16x32_bf16 v[78:81], v[156:159], v[212:215], v[78:81]
	v_mfma_f32_16x16x32_bf16 v[74:77], v[164:167], v[212:215], v[74:77]
	s_setprio 2
	v_mfma_f32_16x16x32_bf16 v[118:121], v[168:171], v[184:187], v[118:121]
	v_mfma_f32_16x16x32_bf16 v[114:117], v[176:179], v[184:187], v[114:117]
	v_mfma_f32_16x16x32_bf16 v[102:105], v[168:171], v[192:195], v[102:105]
	v_mfma_f32_16x16x32_bf16 v[98:101], v[176:179], v[192:195], v[98:101]
	v_mfma_f32_16x16x32_bf16 v[86:89], v[168:171], v[200:203], v[86:89]
	v_mfma_f32_16x16x32_bf16 v[82:85], v[176:179], v[200:203], v[82:85]
	v_mfma_f32_16x16x32_bf16 v[70:73], v[168:171], v[208:211], v[70:73]
	v_mfma_f32_16x16x32_bf16 v[66:69], v[176:179], v[208:211], v[66:69]
	v_mfma_f32_16x16x32_bf16 v[118:121], v[172:175], v[188:191], v[118:121]
	v_mfma_f32_16x16x32_bf16 v[114:117], v[180:183], v[188:191], v[114:117]
	v_mfma_f32_16x16x32_bf16 v[102:105], v[172:175], v[196:199], v[102:105]
	v_mfma_f32_16x16x32_bf16 v[98:101], v[180:183], v[196:199], v[98:101]
	v_mfma_f32_16x16x32_bf16 v[86:89], v[172:175], v[204:207], v[86:89]
	v_mfma_f32_16x16x32_bf16 v[82:85], v[180:183], v[204:207], v[82:85]
	v_mfma_f32_16x16x32_bf16 v[70:73], v[172:175], v[212:215], v[70:73]
	v_mfma_f32_16x16x32_bf16 v[66:69], v[180:183], v[212:215], v[66:69]
	s_barrier
; #define PG8_STAGE(bufoff, gbase, voff) do { _Pragma("unroll") for (int _i = 0; _i < 2; ++_i) \
;         __builtin_amdgcn_global_load_lds((const unsigned*)((const char*)(gbase) + (voff)[_i]), (PG8_LAS unsigned*)(lds + (bufoff) + ldsw + _i * 8192), 16, 0, 0); } while (0)
; #define PG8_LDA(dst, b, h) do { _Pragma("unroll") for (int m = 0; m < 4; ++m) _Pragma("unroll") for (int k = 0; k < 2; ++k) dst[m][k] = *(const PG8_LAS bf16x8*)(lds + PG8_SA(b, h) + aoff + m * 2048 + k * 1024); } while (0)
; #define PG8_LDB(dst, b, h) do { _Pragma("unroll") for (int n = 0; n < 2; ++n) _Pragma("unroll") for (int k = 0; k < 2; ++k) dst[n][k] = *(const PG8_LAS bf16x8*)(lds + PG8_SB(b, h) + boff + n * 2048 + k * 1024); } while (0)
; #define PG8_MMA(ai, bj, At, Bt) do { __builtin_amdgcn_s_setprio(1); _Pragma("unroll") for (int m = 0; m < 4; ++m) _Pragma("unroll") for (int n = 0; n < 2; ++n) _Pragma("unroll") for (int k = 0; k < 2; ++k) \
;         acc[ai][bj][m][n] = __builtin_amdgcn_mfma_f32_16x16x32_bf16(Bt[n][k], At[m][k], acc[ai][bj][m][n], 0, 0, 0); __builtin_amdgcn_s_setprio(0); } while (0)
; #define PG8_WAIT_V(n) asm volatile("s_waitcnt vmcnt(" #n ")" ::: "memory")
; template <class Epi, class Sched, bool ALIGN_EPI = false, bool SP2 = false>
; __device__ __forceinline__ void gemm_phase(PG8_LAS unsigned char* lds, const Gemm g, const Sched& S, const Epi& E) {
;     ...
;             PG8_LDB(B0, 0, 0); PG8_LDB(B1, 0, 1); PG8_SCHED; PG8_LDA(At, 0, 0); PG8_STAGE(PG8_SA(1, 1), a1 + hstep, voffA);
;             PG8_WAIT_V(8); PG8_WAIT_L(0); PG8_BAR; PG8_MMA(0, 0, At, B0); PG8_MMA(0, 1, At, B1); PG8_BAR; PG8_SCHED;
;             PG8_LDA(At, 0, 1); PG8_STAGE(PG8_SB(0, 0), b2, voffB); PG8_STAGE(PG8_SB(0, 1), b2 + hstep, voffB); PG8_STAGE(PG8_SA(0, 0), a2, voffA);
;             PG8_WAIT_V(8); PG8_WAIT_L(0); PG8_BAR; PG8_MMA(1, 0, At, B0); PG8_MMA(1, 1, At, B1); PG8_BAR; PG8_SCHED;
;             PG8_LDB(B0, 1, 0); PG8_LDB(B1, 1, 1); PG8_SCHED; PG8_LDA(At, 1, 0); PG8_STAGE(PG8_SA(0, 1), a2 + hstep, voffA);
;             PG8_WAIT_V(8); PG8_WAIT_L(0); PG8_BAR; PG8_MMA(0, 0, At, B0); PG8_MMA(0, 1, At, B1); PG8_BAR; PG8_SCHED;
;             PG8_LDA(At, 1, 1); PG8_STAGE(PG8_SB(1, 0), b3, voffB); PG8_STAGE(PG8_SB(1, 1), b3 + hstep, voffB); PG8_STAGE(PG8_SA(1, 0), a3, voffA);
;             PG8_WAIT_V(8); PG8_WAIT_L(0); PG8_BAR; PG8_MMA(1, 0, At, B0); PG8_MMA(1, 1, At, B1); PG8_BAR; PG8_SCHED;
	s_setprio 0
	s_add_i32 s40, s55, s33
	v_lshl_add_u64 v[218:219], v[218:219], 0, s[18:19]
	s_mov_b32 m0, s40
	ds_read_b128 v[184:187], v154 offset:49152
	ds_read_b128 v[188:191], v154 offset:50176
	ds_read_b128 v[192:195], v154 offset:51200
	ds_read_b128 v[196:199], v154 offset:52224
	ds_read_b128 v[200:203], v154 offset:53248
	ds_read_b128 v[204:207], v154 offset:54272
	ds_read_b128 v[208:211], v154 offset:55296
	ds_read_b128 v[212:215], v154 offset:56320
	global_load_lds_dwordx4 v[218:219], off
	s_add_i32 m0, s40, 0x2000
	s_add_u32 s38, s38, 0x400080
	v_lshl_add_u64 v[218:219], v[220:221], 0, s[18:19]
	s_addc_u32 s39, s39, 0
	s_add_i32 s40, s56, s33
	global_load_lds_dwordx4 v[218:219], off
	v_lshl_add_u64 v[218:219], s[38:39], 0, v[132:133]
	s_mov_b32 m0, s40
	s_nop 0
	global_load_lds_dwordx4 v[218:219], off
	v_lshl_add_u64 v[218:219], s[38:39], 0, v[136:137]
	s_add_i32 m0, s40, 0x2000
	s_nop 0
	global_load_lds_dwordx4 v[218:219], off
	v_lshl_add_u64 v[218:219], v[222:223], 0, s[18:19]
	s_mov_b32 m0, s48
	s_nop 0
	global_load_lds_dwordx4 v[218:219], off
	v_lshl_add_u64 v[218:219], v[224:225], 0, s[18:19]
	s_mov_b32 m0, s49
	s_nop 0
	global_load_lds_dwordx4 v[218:219], off
	s_waitcnt vmcnt(8)
	s_waitcnt lgkmcnt(0)
	s_setprio 1
	v_mfma_f32_16x16x32_bf16 v[62:65], v[146:149], v[184:187], v[62:65]
	v_mfma_f32_16x16x32_bf16 v[58:61], v[160:163], v[184:187], v[58:61]
	v_mfma_f32_16x16x32_bf16 v[46:49], v[146:149], v[192:195], v[46:49]
	v_mfma_f32_16x16x32_bf16 v[42:45], v[160:163], v[192:195], v[42:45]
	v_mfma_f32_16x16x32_bf16 v[30:33], v[146:149], v[200:203], v[30:33]
	v_mfma_f32_16x16x32_bf16 v[26:29], v[160:163], v[200:203], v[26:29]
	v_mfma_f32_16x16x32_bf16 v[14:17], v[146:149], v[208:211], v[14:17]
	v_mfma_f32_16x16x32_bf16 v[10:13], v[160:163], v[208:211], v[10:13]
	v_mfma_f32_16x16x32_bf16 v[62:65], v[156:159], v[188:191], v[62:65]
	v_mfma_f32_16x16x32_bf16 v[58:61], v[164:167], v[188:191], v[58:61]
	v_mfma_f32_16x16x32_bf16 v[46:49], v[156:159], v[196:199], v[46:49]
	v_mfma_f32_16x16x32_bf16 v[42:45], v[164:167], v[196:199], v[42:45]
	v_mfma_f32_16x16x32_bf16 v[30:33], v[156:159], v[204:207], v[30:33]
	v_mfma_f32_16x16x32_bf16 v[26:29], v[164:167], v[204:207], v[26:29]
	v_mfma_f32_16x16x32_bf16 v[14:17], v[156:159], v[212:215], v[14:17]
	v_mfma_f32_16x16x32_bf16 v[10:13], v[164:167], v[212:215], v[10:13]
	s_setprio 2
	v_mfma_f32_16x16x32_bf16 v[54:57], v[168:171], v[184:187], v[54:57]
	v_mfma_f32_16x16x32_bf16 v[50:53], v[176:179], v[184:187], v[50:53]
	v_mfma_f32_16x16x32_bf16 v[38:41], v[168:171], v[192:195], v[38:41]
	v_mfma_f32_16x16x32_bf16 v[34:37], v[176:179], v[192:195], v[34:37]
	v_mfma_f32_16x16x32_bf16 v[22:25], v[168:171], v[200:203], v[22:25]
	v_mfma_f32_16x16x32_bf16 v[18:21], v[176:179], v[200:203], v[18:21]
	v_mfma_f32_16x16x32_bf16 v[6:9], v[168:171], v[208:211], v[6:9]
	v_mfma_f32_16x16x32_bf16 v[2:5], v[176:179], v[208:211], v[2:5]
	v_mfma_f32_16x16x32_bf16 v[54:57], v[172:175], v[188:191], v[54:57]
	v_mfma_f32_16x16x32_bf16 v[50:53], v[180:183], v[188:191], v[50:53]
	v_mfma_f32_16x16x32_bf16 v[38:41], v[172:175], v[196:199], v[38:41]
	v_mfma_f32_16x16x32_bf16 v[34:37], v[180:183], v[196:199], v[34:37]
	v_mfma_f32_16x16x32_bf16 v[22:25], v[172:175], v[204:207], v[22:25]
	v_mfma_f32_16x16x32_bf16 v[18:21], v[180:183], v[204:207], v[18:21]
	v_mfma_f32_16x16x32_bf16 v[6:9], v[172:175], v[212:215], v[6:9]
	v_mfma_f32_16x16x32_bf16 v[2:5], v[180:183], v[212:215], v[2:5]
	s_barrier
	s_setprio 0
	s_add_i32 s54, s54, 2
	s_add_u32 s36, s36, 0x100
	s_addc_u32 s37, s37, 0
	s_add_u32 s52, s52, 0x100
	s_addc_u32 s53, s53, 0
	s_cmpk_gt_u32 s54, 0xfd
	s_cbranch_scc0 .LBB0_1089
	s_branch .Lmy_p8_kdone
.Lmy_p8_trail:
	ds_read_b128 v[146:149], v152
	ds_read_b128 v[156:159], v152 offset:1024
	ds_read_b128 v[160:163], v152 offset:2048
	ds_read_b128 v[164:167], v152 offset:3072
	ds_read_b128 v[168:171], v153
	ds_read_b128 v[172:175], v153 offset:1024
	ds_read_b128 v[176:179], v153 offset:2048
	ds_read_b128 v[180:183], v153 offset:3072
	s_add_u32 s38, s36, 0xffc00080
	s_addc_u32 s39, s37, -1
	s_cmpk_eq_i32 s54, 0xfc
	s_cselect_b32 s41, s25, s39
	s_cselect_b32 s40, s31, s38
	s_cselect_b32 s39, s23, s53
	s_cselect_b32 s38, s35, s52
	v_lshl_add_u64 v[218:219], s[36:37], 0, v[138:139]
	s_add_i32 m0, s42, 0xc000
	ds_read_b128 v[184:187], v154
	ds_read_b128 v[188:191], v154 offset:1024
	ds_read_b128 v[192:195], v154 offset:2048
	ds_read_b128 v[196:199], v154 offset:3072
	ds_read_b128 v[200:203], v154 offset:4096
	ds_read_b128 v[204:207], v154 offset:5120
	ds_read_b128 v[208:211], v154 offset:6144
	ds_read_b128 v[212:215], v154 offset:7168
	global_load_lds_dwordx4 v[218:219], off
	v_lshl_add_u64 v[218:219], s[36:37], 0, v[140:141]
	s_add_i32 m0, s42, 0xe000
	s_nop 0
	global_load_lds_dwordx4 v[218:219], off
	s_waitcnt vmcnt(8)
	s_waitcnt lgkmcnt(0)
	s_setprio 1
	s_barrier
; #define PG8_STAGE(bufoff, gbase, voff) do { _Pragma("unroll") for (int _i = 0; _i < 2; ++_i) \
;         __builtin_amdgcn_global_load_lds((const unsigned*)((const char*)(gbase) + (voff)[_i]), (PG8_LAS unsigned*)(lds + (bufoff) + ldsw + _i * 8192), 16, 0, 0); } while (0)
; #define PG8_LDA(dst, b, h) do { _Pragma("unroll") for (int m = 0; m < 4; ++m) _Pragma("unroll") for (int k = 0; k < 2; ++k) dst[m][k] = *(const PG8_LAS bf16x8*)(lds + PG8_SA(b, h) + aoff + m * 2048 + k * 1024); } while (0)
; #define PG8_LDB(dst, b, h) do { _Pragma("unroll") for (int n = 0; n < 2; ++n) _Pragma("unroll") for (int k = 0; k < 2; ++k) dst[n][k] = *(const PG8_LAS bf16x8*)(lds + PG8_SB(b, h) + boff + n * 2048 + k * 1024); } while (0)
; #define PG8_MMA(ai, bj, At, Bt) do { __builtin_amdgcn_s_setprio(1); _Pragma("unroll") for (int m = 0; m < 4; ++m) _Pragma("unroll") for (int n = 0; n < 2; ++n) _Pragma("unroll") for (int k = 0; k < 2; ++k) \
;         acc[ai][bj][m][n] = __builtin_amdgcn_mfma_f32_16x16x32_bf16(Bt[n][k], At[m][k], acc[ai][bj][m][n], 0, 0, 0); __builtin_amdgcn_s_setprio(0); } while (0)
; #define PG8_WAIT_V(n) asm volatile("s_waitcnt vmcnt(" #n ")" ::: "memory")
; #define PG8_WAIT_L(n) asm volatile("s_waitcnt lgkmcnt(" #n ")" ::: "memory")
; #define PG8_BAR __builtin_amdgcn_s_barrier()
; #define PG8_SCHED __builtin_amdgcn_sched_barrier(0)
; template <class Epi, class Sched, bool ALIGN_EPI = false, bool SP2 = false>
; __device__ __forceinline__ void gemm_phase(PG8_LAS unsigned char* lds, const Gemm g, const Sched& S, const Epi& E) {
;     ...
;             PG8_LDB(B0, 0, 0); PG8_LDB(B1, 0, 1); PG8_SCHED; PG8_LDA(At, 0, 0); PG8_STAGE(PG8_SA(1, 1), a1 + hstep, voffA);
;             PG8_WAIT_V(8); PG8_WAIT_L(0); PG8_BAR; PG8_MMA(0, 0, At, B0); PG8_MMA(0, 1, At, B1); PG8_BAR; PG8_SCHED;
;             PG8_LDA(At, 0, 1); PG8_STAGE(PG8_SB(0, 0), b2, voffB); PG8_STAGE(PG8_SB(0, 1), b2 + hstep, voffB); PG8_STAGE(PG8_SA(0, 0), a2, voffA);
;             PG8_WAIT_V(8); PG8_WAIT_L(0); PG8_BAR; PG8_MMA(1, 0, At, B0); PG8_MMA(1, 1, At, B1); PG8_BAR; PG8_SCHED;
;             PG8_LDB(B0, 1, 0); PG8_LDB(B1, 1, 1); PG8_SCHED; PG8_LDA(At, 1, 0); PG8_STAGE(PG8_SA(0, 1), a2 + hstep, voffA);
;             PG8_WAIT_V(8); PG8_WAIT_L(0); PG8_BAR; PG8_MMA(0, 0, At, B0); PG8_MMA(0, 1, At, B1); PG8_BAR; PG8_SCHED;
	v_mfma_f32_16x16x32_bf16 v[126:129], v[146:149], v[184:187], v[126:129]
	v_mfma_f32_16x16x32_bf16 v[122:125], v[160:163], v[184:187], v[122:125]
	v_mfma_f32_16x16x32_bf16 v[110:113], v[146:149], v[192:195], v[110:113]
	v_mfma_f32_16x16x32_bf16 v[106:109], v[160:163], v[192:195], v[106:109]
	v_mfma_f32_16x16x32_bf16 v[94:97], v[146:149], v[200:203], v[94:97]
	v_mfma_f32_16x16x32_bf16 v[90:93], v[160:163], v[200:203], v[90:93]
	v_mfma_f32_16x16x32_bf16 v[78:81], v[146:149], v[208:211], v[78:81]
	v_mfma_f32_16x16x32_bf16 v[74:77], v[160:163], v[208:211], v[74:77]
	v_mfma_f32_16x16x32_bf16 v[126:129], v[156:159], v[188:191], v[126:129]
	v_mfma_f32_16x16x32_bf16 v[122:125], v[164:167], v[188:191], v[122:125]
	v_mfma_f32_16x16x32_bf16 v[110:113], v[156:159], v[196:199], v[110:113]
	v_mfma_f32_16x16x32_bf16 v[106:109], v[164:167], v[196:199], v[106:109]
	v_mfma_f32_16x16x32_bf16 v[94:97], v[156:159], v[204:207], v[94:97]
	v_mfma_f32_16x16x32_bf16 v[90:93], v[164:167], v[204:207], v[90:93]
	v_mfma_f32_16x16x32_bf16 v[78:81], v[156:159], v[212:215], v[78:81]
	v_mfma_f32_16x16x32_bf16 v[74:77], v[164:167], v[212:215], v[74:77]
	s_setprio 2
	v_mfma_f32_16x16x32_bf16 v[118:121], v[168:171], v[184:187], v[118:121]
	v_mfma_f32_16x16x32_bf16 v[114:117], v[176:179], v[184:187], v[114:117]
	v_mfma_f32_16x16x32_bf16 v[102:105], v[168:171], v[192:195], v[102:105]
	v_mfma_f32_16x16x32_bf16 v[98:101], v[176:179], v[192:195], v[98:101]
	v_mfma_f32_16x16x32_bf16 v[86:89], v[168:171], v[200:203], v[86:89]
	v_mfma_f32_16x16x32_bf16 v[82:85], v[176:179], v[200:203], v[82:85]
	v_mfma_f32_16x16x32_bf16 v[70:73], v[168:171], v[208:211], v[70:73]
	v_mfma_f32_16x16x32_bf16 v[66:69], v[176:179], v[208:211], v[66:69]
	v_mfma_f32_16x16x32_bf16 v[118:121], v[172:175], v[188:191], v[118:121]
	v_mfma_f32_16x16x32_bf16 v[114:117], v[180:183], v[188:191], v[114:117]
	v_mfma_f32_16x16x32_bf16 v[102:105], v[172:175], v[196:199], v[102:105]
	v_mfma_f32_16x16x32_bf16 v[98:101], v[180:183], v[196:199], v[98:101]
	v_mfma_f32_16x16x32_bf16 v[86:89], v[172:175], v[204:207], v[86:89]
	v_mfma_f32_16x16x32_bf16 v[82:85], v[180:183], v[204:207], v[82:85]
	v_mfma_f32_16x16x32_bf16 v[70:73], v[172:175], v[212:215], v[70:73]
	v_mfma_f32_16x16x32_bf16 v[66:69], v[180:183], v[212:215], v[66:69]
	s_setprio 0
	s_add_i32 s55, s50, s33
	v_lshl_add_u64 v[218:219], s[38:39], 0, v[132:133]
	s_mov_b32 m0, s55
	ds_read_b128 v[184:187], v154 offset:16384
	ds_read_b128 v[188:191], v154 offset:17408
	ds_read_b128 v[192:195], v154 offset:18432
	ds_read_b128 v[196:199], v154 offset:19456
	ds_read_b128 v[200:203], v154 offset:20480
	ds_read_b128 v[204:207], v154 offset:21504
	ds_read_b128 v[208:211], v154 offset:22528
	ds_read_b128 v[212:215], v154 offset:23552
	global_load_lds_dwordx4 v[218:219], off
	s_add_i32 m0, s55, 0x2000
	s_add_u32 s56, s38, 0x400000
	v_lshl_add_u64 v[220:221], s[38:39], 0, v[136:137]
	s_addc_u32 s57, s39, 0
	s_add_i32 s55, s51, s33
	global_load_lds_dwordx4 v[220:221], off
	v_lshl_add_u64 v[222:223], s[56:57], 0, v[132:133]
	s_mov_b32 m0, s55
	v_lshl_add_u64 v[224:225], s[40:41], 0, v[134:135]
	global_load_lds_dwordx4 v[222:223], off
	v_lshl_add_u64 v[222:223], s[56:57], 0, v[136:137]
	s_add_i32 m0, s55, 0x2000
	s_nop 0
	global_load_lds_dwordx4 v[222:223], off
	v_lshl_add_u64 v[222:223], s[40:41], 0, v[130:131]
	s_mov_b32 m0, s42
	s_nop 0
	global_load_lds_dwordx4 v[222:223], off
	s_mov_b32 m0, s43
	s_nop 0
	global_load_lds_dwordx4 v[224:225], off
	s_waitcnt vmcnt(8)
	s_waitcnt lgkmcnt(0)
	s_setprio 1
	s_barrier
	v_mfma_f32_16x16x32_bf16 v[62:65], v[146:149], v[184:187], v[62:65]
	v_mfma_f32_16x16x32_bf16 v[58:61], v[160:163], v[184:187], v[58:61]
	v_mfma_f32_16x16x32_bf16 v[46:49], v[146:149], v[192:195], v[46:49]
	v_mfma_f32_16x16x32_bf16 v[42:45], v[160:163], v[192:195], v[42:45]
	v_mfma_f32_16x16x32_bf16 v[30:33], v[146:149], v[200:203], v[30:33]
	v_mfma_f32_16x16x32_bf16 v[26:29], v[160:163], v[200:203], v[26:29]
	v_mfma_f32_16x16x32_bf16 v[14:17], v[146:149], v[208:211], v[14:17]
	v_mfma_f32_16x16x32_bf16 v[10:13], v[160:163], v[208:211], v[10:13]
	v_mfma_f32_16x16x32_bf16 v[62:65], v[156:159], v[188:191], v[62:65]
	v_mfma_f32_16x16x32_bf16 v[58:61], v[164:167], v[188:191], v[58:61]
	v_mfma_f32_16x16x32_bf16 v[46:49], v[156:159], v[196:199], v[46:49]
	v_mfma_f32_16x16x32_bf16 v[42:45], v[164:167], v[196:199], v[42:45]
	v_mfma_f32_16x16x32_bf16 v[30:33], v[156:159], v[204:207], v[30:33]
	v_mfma_f32_16x16x32_bf16 v[26:29], v[164:167], v[204:207], v[26:29]
	v_mfma_f32_16x16x32_bf16 v[14:17], v[156:159], v[212:215], v[14:17]
	v_mfma_f32_16x16x32_bf16 v[10:13], v[164:167], v[212:215], v[10:13]
	s_setprio 2
	v_mfma_f32_16x16x32_bf16 v[54:57], v[168:171], v[184:187], v[54:57]
	v_mfma_f32_16x16x32_bf16 v[50:53], v[176:179], v[184:187], v[50:53]
	v_mfma_f32_16x16x32_bf16 v[38:41], v[168:171], v[192:195], v[38:41]
	v_mfma_f32_16x16x32_bf16 v[34:37], v[176:179], v[192:195], v[34:37]
	v_mfma_f32_16x16x32_bf16 v[22:25], v[168:171], v[200:203], v[22:25]
	v_mfma_f32_16x16x32_bf16 v[18:21], v[176:179], v[200:203], v[18:21]
	v_mfma_f32_16x16x32_bf16 v[6:9], v[168:171], v[208:211], v[6:9]
	v_mfma_f32_16x16x32_bf16 v[2:5], v[176:179], v[208:211], v[2:5]
	v_mfma_f32_16x16x32_bf16 v[54:57], v[172:175], v[188:191], v[54:57]
	v_mfma_f32_16x16x32_bf16 v[50:53], v[180:183], v[188:191], v[50:53]
	v_mfma_f32_16x16x32_bf16 v[38:41], v[172:175], v[196:199], v[38:41]
	v_mfma_f32_16x16x32_bf16 v[34:37], v[180:183], v[196:199], v[34:37]
	v_mfma_f32_16x16x32_bf16 v[22:25], v[172:175], v[204:207], v[22:25]
	v_mfma_f32_16x16x32_bf16 v[18:21], v[180:183], v[204:207], v[18:21]
	v_mfma_f32_16x16x32_bf16 v[6:9], v[172:175], v[212:215], v[6:9]
	v_mfma_f32_16x16x32_bf16 v[2:5], v[180:183], v[212:215], v[2:5]
	s_setprio 0
	s_add_i32 s55, 0, 0x18000
	s_add_i32 s56, 0, 0x1c000
	v_add_u32_e32 v164, s55, v150
	v_add_u32_e32 v180, s56, v150
	ds_read_b128 v[146:149], v164
	ds_read_b128 v[156:159], v164 offset:1024
	ds_read_b128 v[160:163], v164 offset:2048
	ds_read_b128 v[164:167], v164 offset:3072
	ds_read_b128 v[168:171], v180
	ds_read_b128 v[172:175], v180 offset:1024
	ds_read_b128 v[176:179], v180 offset:2048
	ds_read_b128 v[180:183], v180 offset:3072
	s_add_u32 s40, s40, 0x400000
	s_addc_u32 s41, s41, 0
	s_mov_b32 m0, s44
	v_lshl_add_u64 v[226:227], s[40:41], 0, v[130:131]
	ds_read_b128 v[184:187], v154 offset:32768
	ds_read_b128 v[188:191], v154 offset:33792
	ds_read_b128 v[192:195], v154 offset:34816
	ds_read_b128 v[196:199], v154 offset:35840
	ds_read_b128 v[200:203], v154 offset:36864
	ds_read_b128 v[204:207], v154 offset:37888
	ds_read_b128 v[208:211], v154 offset:38912
	ds_read_b128 v[212:215], v154 offset:39936
	global_load_lds_dwordx4 v[226:227], off
	v_lshl_add_u64 v[226:227], s[40:41], 0, v[134:135]
	s_mov_b32 m0, s45
	s_nop 0
	global_load_lds_dwordx4 v[226:227], off
	s_waitcnt vmcnt(8)
	s_waitcnt lgkmcnt(0)
	s_setprio 1
	s_barrier
; #define PG8_STAGE(bufoff, gbase, voff) do { _Pragma("unroll") for (int _i = 0; _i < 2; ++_i) \
;         __builtin_amdgcn_global_load_lds((const unsigned*)((const char*)(gbase) + (voff)[_i]), (PG8_LAS unsigned*)(lds + (bufoff) + ldsw + _i * 8192), 16, 0, 0); } while (0)
; #define PG8_LDA(dst, b, h) do { _Pragma("unroll") for (int m = 0; m < 4; ++m) _Pragma("unroll") for (int k = 0; k < 2; ++k) dst[m][k] = *(const PG8_LAS bf16x8*)(lds + PG8_SA(b, h) + aoff + m * 2048 + k * 1024); } while (0)
; #define PG8_LDB(dst, b, h) do { _Pragma("unroll") for (int n = 0; n < 2; ++n) _Pragma("unroll") for (int k = 0; k < 2; ++k) dst[n][k] = *(const PG8_LAS bf16x8*)(lds + PG8_SB(b, h) + boff + n * 2048 + k * 1024); } while (0)
; #define PG8_MMA(ai, bj, At, Bt) do { __builtin_amdgcn_s_setprio(1); _Pragma("unroll") for (int m = 0; m < 4; ++m) _Pragma("unroll") for (int n = 0; n < 2; ++n) _Pragma("unroll") for (int k = 0; k < 2; ++k) \
;         acc[ai][bj][m][n] = __builtin_amdgcn_mfma_f32_16x16x32_bf16(Bt[n][k], At[m][k], acc[ai][bj][m][n], 0, 0, 0); __builtin_amdgcn_s_setprio(0); } while (0)
; #define PG8_WAIT_V(n) asm volatile("s_waitcnt vmcnt(" #n ")" ::: "memory")
; #define PG8_WAIT_L(n) asm volatile("s_waitcnt lgkmcnt(" #n ")" ::: "memory")
; #define PG8_BAR __builtin_amdgcn_s_barrier()
; #define PG8_SCHED __builtin_amdgcn_sched_barrier(0)
; template <class Epi, class Sched, bool ALIGN_EPI = false, bool SP2 = false>
; __device__ __forceinline__ void gemm_phase(PG8_LAS unsigned char* lds, const Gemm g, const Sched& S, const Epi& E) {
;     ...
;             PG8_LDB(B0, 1, 0); PG8_LDB(B1, 1, 1); PG8_SCHED; PG8_LDA(At, 1, 0); PG8_STAGE(PG8_SA(0, 1), a2 + hstep, voffA);
;             PG8_WAIT_V(8); PG8_WAIT_L(0); PG8_BAR; PG8_MMA(0, 0, At, B0); PG8_MMA(0, 1, At, B1); PG8_BAR; PG8_SCHED;
;             PG8_LDA(At, 1, 1); PG8_STAGE(PG8_SB(1, 0), b3, voffB); PG8_STAGE(PG8_SB(1, 1), b3 + hstep, voffB); PG8_STAGE(PG8_SA(1, 0), a3, voffA);
;             PG8_WAIT_V(8); PG8_WAIT_L(0); PG8_BAR; PG8_MMA(1, 0, At, B0); PG8_MMA(1, 1, At, B1); PG8_BAR; PG8_SCHED;
;     ...
;         if constexpr (ALIGN_EPI) { if (wr == 0) PG8_BAR; }
	v_mfma_f32_16x16x32_bf16 v[126:129], v[146:149], v[184:187], v[126:129]
	v_mfma_f32_16x16x32_bf16 v[122:125], v[160:163], v[184:187], v[122:125]
	v_mfma_f32_16x16x32_bf16 v[110:113], v[146:149], v[192:195], v[110:113]
	v_mfma_f32_16x16x32_bf16 v[106:109], v[160:163], v[192:195], v[106:109]
	v_mfma_f32_16x16x32_bf16 v[94:97], v[146:149], v[200:203], v[94:97]
	v_mfma_f32_16x16x32_bf16 v[90:93], v[160:163], v[200:203], v[90:93]
	v_mfma_f32_16x16x32_bf16 v[78:81], v[146:149], v[208:211], v[78:81]
	v_mfma_f32_16x16x32_bf16 v[74:77], v[160:163], v[208:211], v[74:77]
	v_mfma_f32_16x16x32_bf16 v[126:129], v[156:159], v[188:191], v[126:129]
	v_mfma_f32_16x16x32_bf16 v[122:125], v[164:167], v[188:191], v[122:125]
	v_mfma_f32_16x16x32_bf16 v[110:113], v[156:159], v[196:199], v[110:113]
	v_mfma_f32_16x16x32_bf16 v[106:109], v[164:167], v[196:199], v[106:109]
	v_mfma_f32_16x16x32_bf16 v[94:97], v[156:159], v[204:207], v[94:97]
	v_mfma_f32_16x16x32_bf16 v[90:93], v[164:167], v[204:207], v[90:93]
	v_mfma_f32_16x16x32_bf16 v[78:81], v[156:159], v[212:215], v[78:81]
	v_mfma_f32_16x16x32_bf16 v[74:77], v[164:167], v[212:215], v[74:77]
	s_setprio 2
	v_mfma_f32_16x16x32_bf16 v[118:121], v[168:171], v[184:187], v[118:121]
	v_mfma_f32_16x16x32_bf16 v[114:117], v[176:179], v[184:187], v[114:117]
	v_mfma_f32_16x16x32_bf16 v[102:105], v[168:171], v[192:195], v[102:105]
	v_mfma_f32_16x16x32_bf16 v[98:101], v[176:179], v[192:195], v[98:101]
	v_mfma_f32_16x16x32_bf16 v[86:89], v[168:171], v[200:203], v[86:89]
	v_mfma_f32_16x16x32_bf16 v[82:85], v[176:179], v[200:203], v[82:85]
	v_mfma_f32_16x16x32_bf16 v[70:73], v[168:171], v[208:211], v[70:73]
	v_mfma_f32_16x16x32_bf16 v[66:69], v[176:179], v[208:211], v[66:69]
	v_mfma_f32_16x16x32_bf16 v[118:121], v[172:175], v[188:191], v[118:121]
	v_mfma_f32_16x16x32_bf16 v[114:117], v[180:183], v[188:191], v[114:117]
	v_mfma_f32_16x16x32_bf16 v[102:105], v[172:175], v[196:199], v[102:105]
	v_mfma_f32_16x16x32_bf16 v[98:101], v[180:183], v[196:199], v[98:101]
	v_mfma_f32_16x16x32_bf16 v[86:89], v[172:175], v[204:207], v[86:89]
	v_mfma_f32_16x16x32_bf16 v[82:85], v[180:183], v[204:207], v[82:85]
	v_mfma_f32_16x16x32_bf16 v[70:73], v[172:175], v[212:215], v[70:73]
	v_mfma_f32_16x16x32_bf16 v[66:69], v[180:183], v[212:215], v[66:69]
	s_setprio 0
	s_add_i32 s40, s55, s33
	v_lshl_add_u64 v[218:219], v[218:219], 0, s[18:19]
	s_mov_b32 m0, s40
	ds_read_b128 v[184:187], v154 offset:49152
	ds_read_b128 v[188:191], v154 offset:50176
	ds_read_b128 v[192:195], v154 offset:51200
	ds_read_b128 v[196:199], v154 offset:52224
	ds_read_b128 v[200:203], v154 offset:53248
	ds_read_b128 v[204:207], v154 offset:54272
	ds_read_b128 v[208:211], v154 offset:55296
	ds_read_b128 v[212:215], v154 offset:56320
	global_load_lds_dwordx4 v[218:219], off
	s_add_i32 m0, s40, 0x2000
	s_add_u32 s38, s38, 0x400080
	v_lshl_add_u64 v[218:219], v[220:221], 0, s[18:19]
	s_addc_u32 s39, s39, 0
	s_add_i32 s40, s56, s33
	global_load_lds_dwordx4 v[218:219], off
	v_lshl_add_u64 v[218:219], s[38:39], 0, v[132:133]
	s_mov_b32 m0, s40
	s_nop 0
	global_load_lds_dwordx4 v[218:219], off
	v_lshl_add_u64 v[218:219], s[38:39], 0, v[136:137]
	s_add_i32 m0, s40, 0x2000
	s_nop 0
	global_load_lds_dwordx4 v[218:219], off
	v_lshl_add_u64 v[218:219], v[222:223], 0, s[18:19]
	s_mov_b32 m0, s48
	s_nop 0
	global_load_lds_dwordx4 v[218:219], off
	v_lshl_add_u64 v[218:219], v[224:225], 0, s[18:19]
	s_mov_b32 m0, s49
	s_nop 0
	global_load_lds_dwordx4 v[218:219], off
	s_waitcnt vmcnt(8)
	s_waitcnt lgkmcnt(0)
	s_setprio 1
	s_barrier
	v_mfma_f32_16x16x32_bf16 v[62:65], v[146:149], v[184:187], v[62:65]
	v_mfma_f32_16x16x32_bf16 v[58:61], v[160:163], v[184:187], v[58:61]
	v_mfma_f32_16x16x32_bf16 v[46:49], v[146:149], v[192:195], v[46:49]
	v_mfma_f32_16x16x32_bf16 v[42:45], v[160:163], v[192:195], v[42:45]
	v_mfma_f32_16x16x32_bf16 v[30:33], v[146:149], v[200:203], v[30:33]
	v_mfma_f32_16x16x32_bf16 v[26:29], v[160:163], v[200:203], v[26:29]
	v_mfma_f32_16x16x32_bf16 v[14:17], v[146:149], v[208:211], v[14:17]
	v_mfma_f32_16x16x32_bf16 v[10:13], v[160:163], v[208:211], v[10:13]
	v_mfma_f32_16x16x32_bf16 v[62:65], v[156:159], v[188:191], v[62:65]
	v_mfma_f32_16x16x32_bf16 v[58:61], v[164:167], v[188:191], v[58:61]
	v_mfma_f32_16x16x32_bf16 v[46:49], v[156:159], v[196:199], v[46:49]
	v_mfma_f32_16x16x32_bf16 v[42:45], v[164:167], v[196:199], v[42:45]
	v_mfma_f32_16x16x32_bf16 v[30:33], v[156:159], v[204:207], v[30:33]
	v_mfma_f32_16x16x32_bf16 v[26:29], v[164:167], v[204:207], v[26:29]
	v_mfma_f32_16x16x32_bf16 v[14:17], v[156:159], v[212:215], v[14:17]
	v_mfma_f32_16x16x32_bf16 v[10:13], v[164:167], v[212:215], v[10:13]
	s_setprio 2
	v_mfma_f32_16x16x32_bf16 v[54:57], v[168:171], v[184:187], v[54:57]
	v_mfma_f32_16x16x32_bf16 v[50:53], v[176:179], v[184:187], v[50:53]
	v_mfma_f32_16x16x32_bf16 v[38:41], v[168:171], v[192:195], v[38:41]
	v_mfma_f32_16x16x32_bf16 v[34:37], v[176:179], v[192:195], v[34:37]
	v_mfma_f32_16x16x32_bf16 v[22:25], v[168:171], v[200:203], v[22:25]
	v_mfma_f32_16x16x32_bf16 v[18:21], v[176:179], v[200:203], v[18:21]
	v_mfma_f32_16x16x32_bf16 v[6:9], v[168:171], v[208:211], v[6:9]
	v_mfma_f32_16x16x32_bf16 v[2:5], v[176:179], v[208:211], v[2:5]
	v_mfma_f32_16x16x32_bf16 v[54:57], v[172:175], v[188:191], v[54:57]
	v_mfma_f32_16x16x32_bf16 v[50:53], v[180:183], v[188:191], v[50:53]
	v_mfma_f32_16x16x32_bf16 v[38:41], v[172:175], v[196:199], v[38:41]
	v_mfma_f32_16x16x32_bf16 v[34:37], v[180:183], v[196:199], v[34:37]
	v_mfma_f32_16x16x32_bf16 v[22:25], v[172:175], v[204:207], v[22:25]
	v_mfma_f32_16x16x32_bf16 v[18:21], v[180:183], v[204:207], v[18:21]
	v_mfma_f32_16x16x32_bf16 v[6:9], v[172:175], v[212:215], v[6:9]
	v_mfma_f32_16x16x32_bf16 v[2:5], v[180:183], v[212:215], v[2:5]
	s_setprio 0
	s_add_i32 s54, s54, 2
	s_add_u32 s36, s36, 0x100
	s_addc_u32 s37, s37, 0
	s_add_u32 s52, s52, 0x100
	s_addc_u32 s53, s53, 0
	s_cmpk_gt_u32 s54, 0xfd
	s_cbranch_scc0 .Lmy_p8_trail
.Lmy_p8_kdone:
	s_and_b64 vcc, exec, s[20:21]
	s_barrier

; #define PG8_BAR __builtin_amdgcn_s_barrier()
; template <class Epi, class Sched, bool ALIGN_EPI = false, bool SP2 = false>
; __device__ __forceinline__ void gemm_phase(PG8_LAS unsigned char* lds, const Gemm g, const Sched& S, const Epi& E) {
;     ...
;         if (!has_next) break;
; #pragma unroll
;         for (int a = 0; a < 2; ++a)
; #pragma unroll
;             for (int b = 0; b < 2; ++b)
; #pragma unroll
;                 for (int m = 0; m < 4; ++m)
; #pragma unroll
;                     for (int n = 0; n < 2; ++n) acc[a][b][m][n] = (f32x4){0.f, 0.f, 0.f, 0.f};
;         cur = nxt; cA = nA; cB = nB; ++ui;
;         if constexpr (ALIGN_EPI) { if (wr == 1) PG8_BAR; }
.LBB0_1108:
	s_or_b64 exec, exec, s[34:35]
	s_andn2_b64 vcc, exec, s[4:5]
	s_mov_b64 s[4:5], -1
	s_cbranch_vccnz .LBB0_1081
	s_andn2_b64 vcc, exec, s[14:15]
	s_cbranch_vccnz .LBB0_1080
	s_branch .LBB0_1080
